# v57 + grid barrier: non-last XCD leaders poll the TOP arrival counter (>= (gen+1)*nx) instead of the last leader's TOPGEN increment (one hop less on release)
# baseline (speedup 1.0000x reference)
; __device__ __forceinline__ unsigned xb_ld(unsigned* p)              { return __hip_atomic_load(p, __ATOMIC_RELAXED, __HIP_MEMORY_SCOPE_AGENT); }
; __device__ __forceinline__ unsigned xb_add(unsigned* p, unsigned v) { return __hip_atomic_fetch_add(p, v, __ATOMIC_RELAXED, __HIP_MEMORY_SCOPE_AGENT); }
; #define XB_SPIN(cond, bar) do { unsigned _sp = 0; while (cond) { __builtin_amdgcn_s_sleep(1); \
;     if ((++_sp & 255u) == 0u) { if (xb_ld(&(bar)[XB_TMO])) break; if (_sp > XB_SPIN_CAP) { atomicAdd(&(bar)[XB_TMO], 1u); break; } } } } while (0)
; __device__ __forceinline__ void xcd_barrier(const XcdBarrier& b) {
;     ...
;         const unsigned old = xb_add(&bar[XB_XSUB(b.x)], 1u);
;         const unsigned gen = old / nloc;
;         if (old + 1u == (gen + 1u) * nloc) {
;             __builtin_amdgcn_fence(__ATOMIC_RELEASE, "agent");
;             asm volatile("s_waitcnt vmcnt(0)" ::: "memory");
;             const unsigned og = xb_add(&bar[XB_TOP], 1u);
;             const unsigned tg = og / nx;
;             if (og + 1u == (tg + 1u) * nx) xb_add(&bar[XB_TOPGEN], 1u);
;             else XB_SPIN(xb_ld(&bar[XB_TOPGEN]) == tg, bar);
.LBB0_593:
	s_or_b64 exec, exec, s[12:13]
	s_waitcnt vmcnt(0)
	v_readfirstlane_b32 s5, v3
	v_sub_u32_e32 v4, 0, v2
	v_readlane_b32 s10, v254, 17
	v_add_u32_e32 v3, s5, v1
	v_cvt_f32_u32_e32 v1, v2
	v_readlane_b32 s11, v254, 18
	s_mov_b64 s[12:13], -1
	v_rcp_iflag_f32_e32 v1, v1
	s_nop 0
	v_mul_f32_e32 v1, 0x4f7ffffe, v1
	v_cvt_u32_f32_e32 v1, v1
	v_mul_lo_u32 v4, v4, v1
	v_mul_hi_u32 v4, v1, v4
	v_add_u32_e32 v1, v1, v4
	v_mul_hi_u32 v1, v3, v1
	v_mul_lo_u32 v4, v1, v2
	v_sub_u32_e32 v4, v3, v4
	v_cmp_ge_u32_e32 vcc, v4, v2
	v_add_u32_e32 v5, 1, v1
	v_add_u32_e32 v3, 1, v3
	v_cndmask_b32_e32 v1, v1, v5, vcc
	v_sub_u32_e32 v5, v4, v2
	v_cndmask_b32_e32 v4, v4, v5, vcc
	v_cmp_ge_u32_e32 vcc, v4, v2
	v_add_u32_e32 v4, 1, v1
	s_nop 0
	v_cndmask_b32_e32 v1, v1, v4, vcc
	v_mul_lo_u32 v4, v2, v1
	v_add_u32_e32 v2, v4, v2
	v_cmp_ne_u32_e32 vcc, v3, v2
	v_mov_b32_e32 v6, v2
	v_mov_b64_e32 v[2:3], s[10:11]
	s_and_saveexec_b64 s[10:11], vcc
	s_cbranch_execz .LBB0_605
	v_readlane_b32 s12, v254, 15
	v_readlane_b32 s13, v254, 16
	s_mov_b64 s[18:19], 0
	s_nop 3
	global_load_dword v2, v203, s[12:13] sc1
	s_waitcnt vmcnt(0)
	v_cmp_lt_u32_e32 vcc, v2, v6
	s_and_saveexec_b64 s[12:13], vcc
	s_cbranch_execz .LBB0_604
	s_mov_b32 s5, 1
	s_branch .LBB0_597

; __device__ __forceinline__ unsigned xb_ld(unsigned* p)              { return __hip_atomic_load(p, __ATOMIC_RELAXED, __HIP_MEMORY_SCOPE_AGENT); }
; #define XB_SPIN(cond, bar) do { unsigned _sp = 0; while (cond) { __builtin_amdgcn_s_sleep(1); \
;     if ((++_sp & 255u) == 0u) { if (xb_ld(&(bar)[XB_TMO])) break; if (_sp > XB_SPIN_CAP) { atomicAdd(&(bar)[XB_TMO], 1u); break; } } } } while (0)
; __device__ __forceinline__ void xcd_barrier(const XcdBarrier& b) {
;     ...
;             else XB_SPIN(xb_ld(&bar[XB_TOPGEN]) == tg, bar);
.LBB0_599:
	v_readlane_b32 s24, v254, 15
	v_readlane_b32 s25, v254, 16
	s_add_i32 s5, s5, 1
	s_mov_b64 s[26:27], -1
	s_nop 2
	global_load_dword v2, v203, s[24:25] sc1
	s_waitcnt vmcnt(0)
	v_cmp_ge_u32_e32 vcc, v2, v6
	s_orn2_b64 s[24:25], vcc, exec
	s_branch .LBB0_596

; __device__ __forceinline__ unsigned xb_ld(unsigned* p)              { return __hip_atomic_load(p, __ATOMIC_RELAXED, __HIP_MEMORY_SCOPE_AGENT); }
; __device__ __forceinline__ unsigned xb_add(unsigned* p, unsigned v) { return __hip_atomic_fetch_add(p, v, __ATOMIC_RELAXED, __HIP_MEMORY_SCOPE_AGENT); }
; #define XB_SPIN(cond, bar) do { unsigned _sp = 0; while (cond) { __builtin_amdgcn_s_sleep(1); \
;     if ((++_sp & 255u) == 0u) { if (xb_ld(&(bar)[XB_TMO])) break; if (_sp > XB_SPIN_CAP) { atomicAdd(&(bar)[XB_TMO], 1u); break; } } } } while (0)
; __device__ __forceinline__ void xcd_barrier(const XcdBarrier& b) {
;     ...
;         const unsigned old = xb_add(&bar[XB_XSUB(b.x)], 1u);
;         const unsigned gen = old / nloc;
;         if (old + 1u == (gen + 1u) * nloc) {
;             __builtin_amdgcn_fence(__ATOMIC_RELEASE, "agent");
;             asm volatile("s_waitcnt vmcnt(0)" ::: "memory");
;             const unsigned og = xb_add(&bar[XB_TOP], 1u);
;             const unsigned tg = og / nx;
;             if (og + 1u == (tg + 1u) * nx) xb_add(&bar[XB_TOPGEN], 1u);
;             else XB_SPIN(xb_ld(&bar[XB_TOPGEN]) == tg, bar);
.LBB0_1963:
	s_or_b64 exec, exec, s[10:11]
	s_waitcnt vmcnt(0)
	v_readfirstlane_b32 s4, v3
	v_sub_u32_e32 v4, 0, v2
	s_mov_b64 s[10:11], -1
	v_add_u32_e32 v3, s4, v1
	v_cvt_f32_u32_e32 v1, v2
	v_readlane_b32 s4, v254, 17
	v_readlane_b32 s5, v254, 18
	v_rcp_iflag_f32_e32 v1, v1
	s_nop 0
	v_mul_f32_e32 v1, 0x4f7ffffe, v1
	v_cvt_u32_f32_e32 v1, v1
	v_mul_lo_u32 v4, v4, v1
	v_mul_hi_u32 v4, v1, v4
	v_add_u32_e32 v1, v1, v4
	v_mul_hi_u32 v1, v3, v1
	v_mul_lo_u32 v4, v1, v2
	v_sub_u32_e32 v4, v3, v4
	v_cmp_ge_u32_e32 vcc, v4, v2
	v_add_u32_e32 v5, 1, v1
	v_add_u32_e32 v3, 1, v3
	v_cndmask_b32_e32 v1, v1, v5, vcc
	v_sub_u32_e32 v5, v4, v2
	v_cndmask_b32_e32 v4, v4, v5, vcc
	v_cmp_ge_u32_e32 vcc, v4, v2
	v_add_u32_e32 v4, 1, v1
	s_nop 0
	v_cndmask_b32_e32 v1, v1, v4, vcc
	v_mul_lo_u32 v4, v2, v1
	v_add_u32_e32 v2, v4, v2
	v_cmp_ne_u32_e32 vcc, v3, v2
	v_mov_b32_e32 v6, v2
	v_mov_b64_e32 v[2:3], s[4:5]
	s_and_saveexec_b64 s[8:9], vcc
	s_cbranch_execz .LBB0_1975
	v_readlane_b32 s4, v254, 15
	v_readlane_b32 s5, v254, 16
	s_mov_b64 s[12:13], 0
	s_nop 3
	global_load_dword v2, v203, s[4:5] sc1
	s_waitcnt vmcnt(0)
	v_cmp_lt_u32_e32 vcc, v2, v6
	s_and_saveexec_b64 s[10:11], vcc
	s_cbranch_execz .LBB0_1974
	s_mov_b32 s4, 1
	s_branch .LBB0_1967

; __device__ __forceinline__ unsigned xb_ld(unsigned* p)              { return __hip_atomic_load(p, __ATOMIC_RELAXED, __HIP_MEMORY_SCOPE_AGENT); }
; #define XB_SPIN(cond, bar) do { unsigned _sp = 0; while (cond) { __builtin_amdgcn_s_sleep(1); \
;     if ((++_sp & 255u) == 0u) { if (xb_ld(&(bar)[XB_TMO])) break; if (_sp > XB_SPIN_CAP) { atomicAdd(&(bar)[XB_TMO], 1u); break; } } } } while (0)
; __device__ __forceinline__ void xcd_barrier(const XcdBarrier& b) {
;     ...
;             else XB_SPIN(xb_ld(&bar[XB_TOPGEN]) == tg, bar);
.LBB0_1969:
	v_readlane_b32 s22, v254, 15
	v_readlane_b32 s23, v254, 16
	s_add_i32 s4, s4, 1
	s_mov_b64 s[24:25], -1
	s_nop 2
	global_load_dword v2, v203, s[22:23] sc1
	s_waitcnt vmcnt(0)
	v_cmp_ge_u32_e32 vcc, v2, v6
	s_orn2_b64 s[22:23], vcc, exec
	s_branch .LBB0_1966
